# GEMM epilogues (DN, OUT bf16 store; GU SwiGLU) rewritten: v_permlane32_swap pairs + global_store_dwordx4 (16 B per lane), pointers computed once
# speedup vs baseline: 1.0283x; 1.0283x over previous
.Lgdn_nolag2:
	s_nop 15
	s_nop 15
	v_add_u32_e32 v132, s14, v181
	v_or_b32_e32 v130, s15, v171
	v_ashrrev_i32_e32 v133, 31, v132
	v_ashrrev_i32_e32 v131, 31, v130
	v_lshlrev_b64 v[130:131], 1, v[130:131]
	v_lshlrev_b64 v[134:135], 11, v[132:133]
	v_lshl_add_u64 v[134:135], s[80:81], 0, v[134:135]
	v_lshl_add_u64 v[134:135], v[134:135], 0, v[130:131]
	v_lshl_add_u64 v[134:135], v[134:135], 0, v[0:1]
	v_lshl_add_u64 v[134:135], v[134:135], 0, v[0:1]
	s_mov_b64 s[2:3], 0x10000
	v_lshl_add_u64 v[136:137], v[134:135], 0, s[2:3]
	v_lshl_add_u64 v[138:139], v[136:137], 0, s[2:3]
	v_lshl_add_u64 v[140:141], v[138:139], 0, s[2:3]
	v_cvt_pk_bf16_f32 v114, v114, v115
	v_cvt_pk_bf16_f32 v115, v116, v117
	v_cvt_pk_bf16_f32 v116, v118, v119
	v_cvt_pk_bf16_f32 v117, v120, v121
	v_cvt_pk_bf16_f32 v118, v122, v123
	v_cvt_pk_bf16_f32 v119, v124, v125
	v_cvt_pk_bf16_f32 v120, v126, v127
	v_cvt_pk_bf16_f32 v121, v128, v129
	v_cvt_pk_bf16_f32 v98, v98, v99
	v_cvt_pk_bf16_f32 v99, v100, v101
	v_cvt_pk_bf16_f32 v100, v102, v103
	v_cvt_pk_bf16_f32 v101, v104, v105
	v_cvt_pk_bf16_f32 v102, v106, v107
	v_cvt_pk_bf16_f32 v103, v108, v109
	v_cvt_pk_bf16_f32 v104, v110, v111
	v_cvt_pk_bf16_f32 v105, v112, v113
	v_permlane32_swap_b32 v114, v116
	v_permlane32_swap_b32 v115, v117
	v_permlane32_swap_b32 v118, v120
	v_permlane32_swap_b32 v119, v121
	global_store_dwordx4 v[134:135], v[114:117], off
	global_store_dwordx4 v[134:135], v[118:121], off offset:32
	v_cvt_pk_bf16_f32 v82, v82, v83
	v_cvt_pk_bf16_f32 v83, v84, v85
	v_cvt_pk_bf16_f32 v84, v86, v87
	v_cvt_pk_bf16_f32 v85, v88, v89
	v_cvt_pk_bf16_f32 v86, v90, v91
	v_cvt_pk_bf16_f32 v87, v92, v93
	v_cvt_pk_bf16_f32 v88, v94, v95
	v_cvt_pk_bf16_f32 v89, v96, v97
	v_permlane32_swap_b32 v98, v100
	v_permlane32_swap_b32 v99, v101
	v_permlane32_swap_b32 v102, v104
	v_permlane32_swap_b32 v103, v105
	global_store_dwordx4 v[134:135], v[98:101], off offset:64
	global_store_dwordx4 v[134:135], v[102:105], off offset:96
	v_cvt_pk_bf16_f32 v66, v66, v67
	v_cvt_pk_bf16_f32 v67, v68, v69
	v_cvt_pk_bf16_f32 v68, v70, v71
	v_cvt_pk_bf16_f32 v69, v72, v73
	v_cvt_pk_bf16_f32 v70, v74, v75
	v_cvt_pk_bf16_f32 v71, v76, v77
	v_cvt_pk_bf16_f32 v72, v78, v79
	v_cvt_pk_bf16_f32 v73, v80, v81
	v_permlane32_swap_b32 v82, v84
	v_permlane32_swap_b32 v83, v85
	v_permlane32_swap_b32 v86, v88
	v_permlane32_swap_b32 v87, v89
	global_store_dwordx4 v[136:137], v[82:85], off
	global_store_dwordx4 v[136:137], v[86:89], off offset:32
	v_cvt_pk_bf16_f32 v50, v50, v51
	v_cvt_pk_bf16_f32 v51, v52, v53
	v_cvt_pk_bf16_f32 v52, v54, v55
	v_cvt_pk_bf16_f32 v53, v56, v57
	v_cvt_pk_bf16_f32 v54, v58, v59
	v_cvt_pk_bf16_f32 v55, v60, v61
	v_cvt_pk_bf16_f32 v56, v62, v63
	v_cvt_pk_bf16_f32 v57, v64, v65
	v_permlane32_swap_b32 v66, v68
	v_permlane32_swap_b32 v67, v69
	v_permlane32_swap_b32 v70, v72
	v_permlane32_swap_b32 v71, v73
	global_store_dwordx4 v[136:137], v[66:69], off offset:64
	global_store_dwordx4 v[136:137], v[70:73], off offset:96
	v_cvt_pk_bf16_f32 v34, v34, v35
	v_cvt_pk_bf16_f32 v35, v36, v37
	v_cvt_pk_bf16_f32 v36, v38, v39
	v_cvt_pk_bf16_f32 v37, v40, v41
	v_cvt_pk_bf16_f32 v38, v42, v43
	v_cvt_pk_bf16_f32 v39, v44, v45
	v_cvt_pk_bf16_f32 v40, v46, v47
	v_cvt_pk_bf16_f32 v41, v48, v49
	v_permlane32_swap_b32 v50, v52
	v_permlane32_swap_b32 v51, v53
	v_permlane32_swap_b32 v54, v56
	v_permlane32_swap_b32 v55, v57
	global_store_dwordx4 v[138:139], v[50:53], off
	global_store_dwordx4 v[138:139], v[54:57], off offset:32
	v_cvt_pk_bf16_f32 v18, v18, v19
	v_cvt_pk_bf16_f32 v19, v20, v21
	v_cvt_pk_bf16_f32 v20, v22, v23
	v_cvt_pk_bf16_f32 v21, v24, v25
	v_cvt_pk_bf16_f32 v22, v26, v27
	v_cvt_pk_bf16_f32 v23, v28, v29
	v_cvt_pk_bf16_f32 v24, v30, v31
	v_cvt_pk_bf16_f32 v25, v32, v33
	v_permlane32_swap_b32 v34, v36
	v_permlane32_swap_b32 v35, v37
	v_permlane32_swap_b32 v38, v40
	v_permlane32_swap_b32 v39, v41
	global_store_dwordx4 v[138:139], v[34:37], off offset:64
	global_store_dwordx4 v[138:139], v[38:41], off offset:96
	v_cvt_pk_bf16_f32 v2, v2, v3
	v_cvt_pk_bf16_f32 v3, v4, v5
	v_cvt_pk_bf16_f32 v4, v6, v7
	v_cvt_pk_bf16_f32 v5, v8, v9
	v_cvt_pk_bf16_f32 v6, v10, v11
	v_cvt_pk_bf16_f32 v7, v12, v13
	v_cvt_pk_bf16_f32 v8, v14, v15
	v_cvt_pk_bf16_f32 v9, v16, v17
	v_permlane32_swap_b32 v18, v20
	v_permlane32_swap_b32 v19, v21
	v_permlane32_swap_b32 v22, v24
	v_permlane32_swap_b32 v23, v25
	global_store_dwordx4 v[140:141], v[18:21], off
	global_store_dwordx4 v[140:141], v[22:25], off offset:32
	s_nop 1
	v_permlane32_swap_b32 v2, v4
	v_permlane32_swap_b32 v3, v5
	v_permlane32_swap_b32 v6, v8
	v_permlane32_swap_b32 v7, v9
	global_store_dwordx4 v[140:141], v[2:5], off offset:64
	global_store_dwordx4 v[140:141], v[6:9], off offset:96
	s_add_i32 s10, s10, s46
	v_readlane_b32 s2, v254, 52
	s_nop 3
	v_subrev_u32_e32 v190, s2, v190
	s_cmpk_gt_i32 s10, 0xff
	s_cbranch_scc0 .LBB0_40

.Lggu_nolag2:
	s_nop 15
	s_nop 15
	v_add_u32_e32 v132, s14, v182
	v_or_b32_e32 v130, s15, v173
	v_ashrrev_i32_e32 v130, 1, v130
	v_ashrrev_i32_e32 v131, 31, v130
	v_lshlrev_b64 v[130:131], 1, v[130:131]
	v_mov_b64_e32 v[142:143], s[40:41]
	v_mad_i64_i32 v[134:135], s[2:3], v132, s5, v[142:143]
	v_lshl_add_u64 v[134:135], v[134:135], 0, v[130:131]
	v_lshl_add_u64 v[134:135], v[134:135], 0, v[0:1]
	v_lshl_add_u64 v[134:135], v[134:135], 0, v[0:1]
	s_mov_b64 s[2:3], 0x2c000
	v_lshl_add_u64 v[136:137], v[134:135], 0, s[2:3]
	v_lshl_add_u64 v[138:139], v[136:137], 0, s[2:3]
	v_lshl_add_u64 v[140:141], v[138:139], 0, s[2:3]
	v_mul_f32_e32 v144, 0xbfb8aa3b, v114
	v_mul_f32_e32 v145, 0xbfb8aa3b, v115
	v_mul_f32_e32 v146, 0xbfb8aa3b, v116
	v_mul_f32_e32 v147, 0xbfb8aa3b, v117
	v_exp_f32_e32 v144, v144
	v_exp_f32_e32 v145, v145
	v_exp_f32_e32 v146, v146
	v_exp_f32_e32 v147, v147
	v_add_f32_e32 v144, 1.0, v144
	v_add_f32_e32 v145, 1.0, v145
	v_add_f32_e32 v146, 1.0, v146
	v_add_f32_e32 v147, 1.0, v147
	v_rcp_f32_e32 v144, v144
	v_rcp_f32_e32 v145, v145
	v_rcp_f32_e32 v146, v146
	v_rcp_f32_e32 v147, v147
	v_mul_f32_e32 v114, v114, v144
	v_mul_f32_e32 v115, v115, v145
	v_mul_f32_e32 v116, v116, v146
	v_mul_f32_e32 v117, v117, v147
	v_mul_f32_e32 v114, v98, v114
	v_mul_f32_e32 v115, v99, v115
	v_mul_f32_e32 v116, v100, v116
	v_mul_f32_e32 v117, v101, v117
	v_mul_f32_e32 v144, 0xbfb8aa3b, v118
	v_mul_f32_e32 v145, 0xbfb8aa3b, v119
	v_mul_f32_e32 v146, 0xbfb8aa3b, v120
	v_mul_f32_e32 v147, 0xbfb8aa3b, v121
	v_exp_f32_e32 v144, v144
	v_exp_f32_e32 v145, v145
	v_exp_f32_e32 v146, v146
	v_exp_f32_e32 v147, v147
	v_add_f32_e32 v144, 1.0, v144
	v_add_f32_e32 v145, 1.0, v145
	v_add_f32_e32 v146, 1.0, v146
	v_add_f32_e32 v147, 1.0, v147
	v_rcp_f32_e32 v144, v144
	v_rcp_f32_e32 v145, v145
	v_rcp_f32_e32 v146, v146
	v_rcp_f32_e32 v147, v147
	v_mul_f32_e32 v118, v118, v144
	v_mul_f32_e32 v119, v119, v145
	v_mul_f32_e32 v120, v120, v146
	v_mul_f32_e32 v121, v121, v147
	v_mul_f32_e32 v118, v102, v118
	v_mul_f32_e32 v119, v103, v119
	v_mul_f32_e32 v120, v104, v120
	v_mul_f32_e32 v121, v105, v121
	v_mul_f32_e32 v144, 0xbfb8aa3b, v122
	v_mul_f32_e32 v145, 0xbfb8aa3b, v123
	v_mul_f32_e32 v146, 0xbfb8aa3b, v124
	v_mul_f32_e32 v147, 0xbfb8aa3b, v125
	v_exp_f32_e32 v144, v144
	v_exp_f32_e32 v145, v145
	v_exp_f32_e32 v146, v146
	v_exp_f32_e32 v147, v147
	v_add_f32_e32 v144, 1.0, v144
	v_add_f32_e32 v145, 1.0, v145
	v_add_f32_e32 v146, 1.0, v146
	v_add_f32_e32 v147, 1.0, v147
	v_rcp_f32_e32 v144, v144
	v_rcp_f32_e32 v145, v145
	v_rcp_f32_e32 v146, v146
	v_rcp_f32_e32 v147, v147
	v_mul_f32_e32 v122, v122, v144
	v_mul_f32_e32 v123, v123, v145
	v_mul_f32_e32 v124, v124, v146
	v_mul_f32_e32 v125, v125, v147
	v_mul_f32_e32 v122, v106, v122
	v_mul_f32_e32 v123, v107, v123
	v_mul_f32_e32 v124, v108, v124
	v_mul_f32_e32 v125, v109, v125
	v_mul_f32_e32 v144, 0xbfb8aa3b, v126
	v_mul_f32_e32 v145, 0xbfb8aa3b, v127
	v_mul_f32_e32 v146, 0xbfb8aa3b, v128
	v_mul_f32_e32 v147, 0xbfb8aa3b, v129
	v_exp_f32_e32 v144, v144
	v_exp_f32_e32 v145, v145
	v_exp_f32_e32 v146, v146
	v_exp_f32_e32 v147, v147
	v_add_f32_e32 v144, 1.0, v144
	v_add_f32_e32 v145, 1.0, v145
	v_add_f32_e32 v146, 1.0, v146
	v_add_f32_e32 v147, 1.0, v147
	v_rcp_f32_e32 v144, v144
	v_rcp_f32_e32 v145, v145
	v_rcp_f32_e32 v146, v146
	v_rcp_f32_e32 v147, v147
	v_mul_f32_e32 v126, v126, v144
	v_mul_f32_e32 v127, v127, v145
	v_mul_f32_e32 v128, v128, v146
	v_mul_f32_e32 v129, v129, v147
	v_mul_f32_e32 v126, v110, v126
	v_mul_f32_e32 v127, v111, v127
	v_mul_f32_e32 v128, v112, v128
	v_mul_f32_e32 v129, v113, v129
	v_cvt_pk_bf16_f32 v114, v114, v115
	v_cvt_pk_bf16_f32 v115, v116, v117
	v_cvt_pk_bf16_f32 v116, v118, v119
	v_cvt_pk_bf16_f32 v117, v120, v121
	v_cvt_pk_bf16_f32 v118, v122, v123
	v_cvt_pk_bf16_f32 v119, v124, v125
	v_cvt_pk_bf16_f32 v120, v126, v127
	v_cvt_pk_bf16_f32 v121, v128, v129
	v_mul_f32_e32 v144, 0xbfb8aa3b, v82
	v_mul_f32_e32 v145, 0xbfb8aa3b, v83
	v_mul_f32_e32 v146, 0xbfb8aa3b, v84
	v_mul_f32_e32 v147, 0xbfb8aa3b, v85
	v_exp_f32_e32 v144, v144
	v_exp_f32_e32 v145, v145
	v_exp_f32_e32 v146, v146
	v_exp_f32_e32 v147, v147
	v_add_f32_e32 v144, 1.0, v144
	v_add_f32_e32 v145, 1.0, v145
	v_add_f32_e32 v146, 1.0, v146
	v_add_f32_e32 v147, 1.0, v147
	v_rcp_f32_e32 v144, v144
	v_rcp_f32_e32 v145, v145
	v_rcp_f32_e32 v146, v146
	v_rcp_f32_e32 v147, v147
	v_mul_f32_e32 v82, v82, v144
	v_mul_f32_e32 v83, v83, v145
	v_mul_f32_e32 v84, v84, v146
	v_mul_f32_e32 v85, v85, v147
	v_mul_f32_e32 v82, v66, v82
	v_mul_f32_e32 v83, v67, v83
	v_mul_f32_e32 v84, v68, v84
	v_mul_f32_e32 v85, v69, v85
	v_mul_f32_e32 v144, 0xbfb8aa3b, v86
	v_mul_f32_e32 v145, 0xbfb8aa3b, v87
	v_mul_f32_e32 v146, 0xbfb8aa3b, v88
	v_mul_f32_e32 v147, 0xbfb8aa3b, v89
	v_exp_f32_e32 v144, v144
	v_exp_f32_e32 v145, v145
	v_exp_f32_e32 v146, v146
	v_exp_f32_e32 v147, v147
	v_add_f32_e32 v144, 1.0, v144
	v_add_f32_e32 v145, 1.0, v145
	v_add_f32_e32 v146, 1.0, v146
	v_add_f32_e32 v147, 1.0, v147
	v_rcp_f32_e32 v144, v144
	v_rcp_f32_e32 v145, v145
	v_rcp_f32_e32 v146, v146
	v_rcp_f32_e32 v147, v147
	v_mul_f32_e32 v86, v86, v144
	v_mul_f32_e32 v87, v87, v145
	v_mul_f32_e32 v88, v88, v146
	v_mul_f32_e32 v89, v89, v147
	v_mul_f32_e32 v86, v70, v86
	v_mul_f32_e32 v87, v71, v87
	v_mul_f32_e32 v88, v72, v88
	v_mul_f32_e32 v89, v73, v89
	v_mul_f32_e32 v144, 0xbfb8aa3b, v90
	v_mul_f32_e32 v145, 0xbfb8aa3b, v91
	v_mul_f32_e32 v146, 0xbfb8aa3b, v92
	v_mul_f32_e32 v147, 0xbfb8aa3b, v93
	v_exp_f32_e32 v144, v144
	v_exp_f32_e32 v145, v145
	v_exp_f32_e32 v146, v146
	v_exp_f32_e32 v147, v147
	v_add_f32_e32 v144, 1.0, v144
	v_add_f32_e32 v145, 1.0, v145
	v_add_f32_e32 v146, 1.0, v146
	v_add_f32_e32 v147, 1.0, v147
	v_rcp_f32_e32 v144, v144
	v_rcp_f32_e32 v145, v145
	v_rcp_f32_e32 v146, v146
	v_rcp_f32_e32 v147, v147
	v_mul_f32_e32 v90, v90, v144
	v_mul_f32_e32 v91, v91, v145
	v_mul_f32_e32 v92, v92, v146
	v_mul_f32_e32 v93, v93, v147
	v_mul_f32_e32 v90, v74, v90
	v_mul_f32_e32 v91, v75, v91
	v_mul_f32_e32 v92, v76, v92
	v_mul_f32_e32 v93, v77, v93
	v_mul_f32_e32 v144, 0xbfb8aa3b, v94
	v_mul_f32_e32 v145, 0xbfb8aa3b, v95
	v_mul_f32_e32 v146, 0xbfb8aa3b, v96
	v_mul_f32_e32 v147, 0xbfb8aa3b, v97
	v_exp_f32_e32 v144, v144
	v_exp_f32_e32 v145, v145
	v_exp_f32_e32 v146, v146
	v_exp_f32_e32 v147, v147
	v_add_f32_e32 v144, 1.0, v144
	v_add_f32_e32 v145, 1.0, v145
	v_add_f32_e32 v146, 1.0, v146
	v_add_f32_e32 v147, 1.0, v147
	v_rcp_f32_e32 v144, v144
	v_rcp_f32_e32 v145, v145
	v_rcp_f32_e32 v146, v146
	v_rcp_f32_e32 v147, v147
	v_mul_f32_e32 v94, v94, v144
	v_mul_f32_e32 v95, v95, v145
	v_mul_f32_e32 v96, v96, v146
	v_mul_f32_e32 v97, v97, v147
	v_mul_f32_e32 v94, v78, v94
	v_mul_f32_e32 v95, v79, v95
	v_mul_f32_e32 v96, v80, v96
	v_mul_f32_e32 v97, v81, v97
	v_permlane32_swap_b32 v114, v116
	v_permlane32_swap_b32 v115, v117
	v_permlane32_swap_b32 v118, v120
	v_permlane32_swap_b32 v119, v121
	global_store_dwordx4 v[134:135], v[114:117], off
	global_store_dwordx4 v[134:135], v[118:121], off offset:32
	v_cvt_pk_bf16_f32 v82, v82, v83
	v_cvt_pk_bf16_f32 v83, v84, v85
	v_cvt_pk_bf16_f32 v84, v86, v87
	v_cvt_pk_bf16_f32 v85, v88, v89
	v_cvt_pk_bf16_f32 v86, v90, v91
	v_cvt_pk_bf16_f32 v87, v92, v93
	v_cvt_pk_bf16_f32 v88, v94, v95
	v_cvt_pk_bf16_f32 v89, v96, v97
	v_mul_f32_e32 v144, 0xbfb8aa3b, v50
	v_mul_f32_e32 v145, 0xbfb8aa3b, v51
	v_mul_f32_e32 v146, 0xbfb8aa3b, v52
	v_mul_f32_e32 v147, 0xbfb8aa3b, v53
	v_exp_f32_e32 v144, v144
	v_exp_f32_e32 v145, v145
	v_exp_f32_e32 v146, v146
	v_exp_f32_e32 v147, v147
	v_add_f32_e32 v144, 1.0, v144
	v_add_f32_e32 v145, 1.0, v145
	v_add_f32_e32 v146, 1.0, v146
	v_add_f32_e32 v147, 1.0, v147
	v_rcp_f32_e32 v144, v144
	v_rcp_f32_e32 v145, v145
	v_rcp_f32_e32 v146, v146
	v_rcp_f32_e32 v147, v147
	v_mul_f32_e32 v50, v50, v144
	v_mul_f32_e32 v51, v51, v145
	v_mul_f32_e32 v52, v52, v146
	v_mul_f32_e32 v53, v53, v147
	v_mul_f32_e32 v50, v34, v50
	v_mul_f32_e32 v51, v35, v51
	v_mul_f32_e32 v52, v36, v52
	v_mul_f32_e32 v53, v37, v53
	v_mul_f32_e32 v144, 0xbfb8aa3b, v54
	v_mul_f32_e32 v145, 0xbfb8aa3b, v55
	v_mul_f32_e32 v146, 0xbfb8aa3b, v56
	v_mul_f32_e32 v147, 0xbfb8aa3b, v57
	v_exp_f32_e32 v144, v144
	v_exp_f32_e32 v145, v145
	v_exp_f32_e32 v146, v146
	v_exp_f32_e32 v147, v147
	v_add_f32_e32 v144, 1.0, v144
	v_add_f32_e32 v145, 1.0, v145
	v_add_f32_e32 v146, 1.0, v146
	v_add_f32_e32 v147, 1.0, v147
	v_rcp_f32_e32 v144, v144
	v_rcp_f32_e32 v145, v145
	v_rcp_f32_e32 v146, v146
	v_rcp_f32_e32 v147, v147
	v_mul_f32_e32 v54, v54, v144
	v_mul_f32_e32 v55, v55, v145
	v_mul_f32_e32 v56, v56, v146
	v_mul_f32_e32 v57, v57, v147
	v_mul_f32_e32 v54, v38, v54
	v_mul_f32_e32 v55, v39, v55
	v_mul_f32_e32 v56, v40, v56
	v_mul_f32_e32 v57, v41, v57
	v_mul_f32_e32 v144, 0xbfb8aa3b, v58
	v_mul_f32_e32 v145, 0xbfb8aa3b, v59
	v_mul_f32_e32 v146, 0xbfb8aa3b, v60
	v_mul_f32_e32 v147, 0xbfb8aa3b, v61
	v_exp_f32_e32 v144, v144
	v_exp_f32_e32 v145, v145
	v_exp_f32_e32 v146, v146
	v_exp_f32_e32 v147, v147
	v_add_f32_e32 v144, 1.0, v144
	v_add_f32_e32 v145, 1.0, v145
	v_add_f32_e32 v146, 1.0, v146
	v_add_f32_e32 v147, 1.0, v147
	v_rcp_f32_e32 v144, v144
	v_rcp_f32_e32 v145, v145
	v_rcp_f32_e32 v146, v146
	v_rcp_f32_e32 v147, v147
	v_mul_f32_e32 v58, v58, v144
	v_mul_f32_e32 v59, v59, v145
	v_mul_f32_e32 v60, v60, v146
	v_mul_f32_e32 v61, v61, v147
	v_mul_f32_e32 v58, v42, v58
	v_mul_f32_e32 v59, v43, v59
	v_mul_f32_e32 v60, v44, v60
	v_mul_f32_e32 v61, v45, v61
	v_mul_f32_e32 v144, 0xbfb8aa3b, v62
	v_mul_f32_e32 v145, 0xbfb8aa3b, v63
	v_mul_f32_e32 v146, 0xbfb8aa3b, v64
	v_mul_f32_e32 v147, 0xbfb8aa3b, v65
	v_exp_f32_e32 v144, v144
	v_exp_f32_e32 v145, v145
	v_exp_f32_e32 v146, v146
	v_exp_f32_e32 v147, v147
	v_add_f32_e32 v144, 1.0, v144
	v_add_f32_e32 v145, 1.0, v145
	v_add_f32_e32 v146, 1.0, v146
	v_add_f32_e32 v147, 1.0, v147
	v_rcp_f32_e32 v144, v144
	v_rcp_f32_e32 v145, v145
	v_rcp_f32_e32 v146, v146
	v_rcp_f32_e32 v147, v147
	v_mul_f32_e32 v62, v62, v144
	v_mul_f32_e32 v63, v63, v145
	v_mul_f32_e32 v64, v64, v146
	v_mul_f32_e32 v65, v65, v147
	v_mul_f32_e32 v62, v46, v62
	v_mul_f32_e32 v63, v47, v63
	v_mul_f32_e32 v64, v48, v64
	v_mul_f32_e32 v65, v49, v65
	v_permlane32_swap_b32 v82, v84
	v_permlane32_swap_b32 v83, v85
	v_permlane32_swap_b32 v86, v88
	v_permlane32_swap_b32 v87, v89
	global_store_dwordx4 v[136:137], v[82:85], off
	global_store_dwordx4 v[136:137], v[86:89], off offset:32
	v_cvt_pk_bf16_f32 v50, v50, v51
	v_cvt_pk_bf16_f32 v51, v52, v53
	v_cvt_pk_bf16_f32 v52, v54, v55
	v_cvt_pk_bf16_f32 v53, v56, v57
	v_cvt_pk_bf16_f32 v54, v58, v59
	v_cvt_pk_bf16_f32 v55, v60, v61
	v_cvt_pk_bf16_f32 v56, v62, v63
	v_cvt_pk_bf16_f32 v57, v64, v65
	v_mul_f32_e32 v144, 0xbfb8aa3b, v18
	v_mul_f32_e32 v145, 0xbfb8aa3b, v19
	v_mul_f32_e32 v146, 0xbfb8aa3b, v20
	v_mul_f32_e32 v147, 0xbfb8aa3b, v21
	v_exp_f32_e32 v144, v144
	v_exp_f32_e32 v145, v145
	v_exp_f32_e32 v146, v146
	v_exp_f32_e32 v147, v147
	v_add_f32_e32 v144, 1.0, v144
	v_add_f32_e32 v145, 1.0, v145
	v_add_f32_e32 v146, 1.0, v146
	v_add_f32_e32 v147, 1.0, v147
	v_rcp_f32_e32 v144, v144
	v_rcp_f32_e32 v145, v145
	v_rcp_f32_e32 v146, v146
	v_rcp_f32_e32 v147, v147
	v_mul_f32_e32 v18, v18, v144
	v_mul_f32_e32 v19, v19, v145
	v_mul_f32_e32 v20, v20, v146
	v_mul_f32_e32 v21, v21, v147
	v_mul_f32_e32 v18, v2, v18
	v_mul_f32_e32 v19, v3, v19
	v_mul_f32_e32 v20, v4, v20
	v_mul_f32_e32 v21, v5, v21
	v_mul_f32_e32 v144, 0xbfb8aa3b, v22
	v_mul_f32_e32 v145, 0xbfb8aa3b, v23
	v_mul_f32_e32 v146, 0xbfb8aa3b, v24
	v_mul_f32_e32 v147, 0xbfb8aa3b, v25
	v_exp_f32_e32 v144, v144
	v_exp_f32_e32 v145, v145
	v_exp_f32_e32 v146, v146
	v_exp_f32_e32 v147, v147
	v_add_f32_e32 v144, 1.0, v144
	v_add_f32_e32 v145, 1.0, v145
	v_add_f32_e32 v146, 1.0, v146
	v_add_f32_e32 v147, 1.0, v147
	v_rcp_f32_e32 v144, v144
	v_rcp_f32_e32 v145, v145
	v_rcp_f32_e32 v146, v146
	v_rcp_f32_e32 v147, v147
	v_mul_f32_e32 v22, v22, v144
	v_mul_f32_e32 v23, v23, v145
	v_mul_f32_e32 v24, v24, v146
	v_mul_f32_e32 v25, v25, v147
	v_mul_f32_e32 v22, v6, v22
	v_mul_f32_e32 v23, v7, v23
	v_mul_f32_e32 v24, v8, v24
	v_mul_f32_e32 v25, v9, v25
	v_mul_f32_e32 v144, 0xbfb8aa3b, v26
	v_mul_f32_e32 v145, 0xbfb8aa3b, v27
	v_mul_f32_e32 v146, 0xbfb8aa3b, v28
	v_mul_f32_e32 v147, 0xbfb8aa3b, v29
	v_exp_f32_e32 v144, v144
	v_exp_f32_e32 v145, v145
	v_exp_f32_e32 v146, v146
	v_exp_f32_e32 v147, v147
	v_add_f32_e32 v144, 1.0, v144
	v_add_f32_e32 v145, 1.0, v145
	v_add_f32_e32 v146, 1.0, v146
	v_add_f32_e32 v147, 1.0, v147
	v_rcp_f32_e32 v144, v144
	v_rcp_f32_e32 v145, v145
	v_rcp_f32_e32 v146, v146
	v_rcp_f32_e32 v147, v147
	v_mul_f32_e32 v26, v26, v144
	v_mul_f32_e32 v27, v27, v145
	v_mul_f32_e32 v28, v28, v146
	v_mul_f32_e32 v29, v29, v147
	v_mul_f32_e32 v26, v10, v26
	v_mul_f32_e32 v27, v11, v27
	v_mul_f32_e32 v28, v12, v28
	v_mul_f32_e32 v29, v13, v29
	v_mul_f32_e32 v144, 0xbfb8aa3b, v30
	v_mul_f32_e32 v145, 0xbfb8aa3b, v31
	v_mul_f32_e32 v146, 0xbfb8aa3b, v32
	v_mul_f32_e32 v147, 0xbfb8aa3b, v33
	v_exp_f32_e32 v144, v144
	v_exp_f32_e32 v145, v145
	v_exp_f32_e32 v146, v146
	v_exp_f32_e32 v147, v147
	v_add_f32_e32 v144, 1.0, v144
	v_add_f32_e32 v145, 1.0, v145
	v_add_f32_e32 v146, 1.0, v146
	v_add_f32_e32 v147, 1.0, v147
	v_rcp_f32_e32 v144, v144
	v_rcp_f32_e32 v145, v145
	v_rcp_f32_e32 v146, v146
	v_rcp_f32_e32 v147, v147
	v_mul_f32_e32 v30, v30, v144
	v_mul_f32_e32 v31, v31, v145
	v_mul_f32_e32 v32, v32, v146
	v_mul_f32_e32 v33, v33, v147
	v_mul_f32_e32 v30, v14, v30
	v_mul_f32_e32 v31, v15, v31
	v_mul_f32_e32 v32, v16, v32
	v_mul_f32_e32 v33, v17, v33
	v_permlane32_swap_b32 v50, v52
	v_permlane32_swap_b32 v51, v53
	v_permlane32_swap_b32 v54, v56
	v_permlane32_swap_b32 v55, v57
	global_store_dwordx4 v[138:139], v[50:53], off
	global_store_dwordx4 v[138:139], v[54:57], off offset:32
	v_cvt_pk_bf16_f32 v18, v18, v19
	v_cvt_pk_bf16_f32 v19, v20, v21
	v_cvt_pk_bf16_f32 v20, v22, v23
	v_cvt_pk_bf16_f32 v21, v24, v25
	v_cvt_pk_bf16_f32 v22, v26, v27
	v_cvt_pk_bf16_f32 v23, v28, v29
	v_cvt_pk_bf16_f32 v24, v30, v31
	v_cvt_pk_bf16_f32 v25, v32, v33
	s_nop 1
	v_permlane32_swap_b32 v18, v20
	v_permlane32_swap_b32 v19, v21
	v_permlane32_swap_b32 v22, v24
	v_permlane32_swap_b32 v23, v25
	global_store_dwordx4 v[140:141], v[18:21], off
	global_store_dwordx4 v[140:141], v[22:25], off offset:32
	s_add_i32 s10, s10, s46
	s_cmp_ge_i32 s10, s1
	s_cbranch_scc0 .LBB0_53

.Lgou_nolag2:
	s_nop 15
	s_nop 15
	v_add_u32_e32 v132, s1, v182
	v_or_b32_e32 v130, s10, v173
	v_ashrrev_i32_e32 v133, 31, v132
	v_ashrrev_i32_e32 v131, 31, v130
	v_lshlrev_b64 v[130:131], 1, v[130:131]
	v_lshlrev_b64 v[134:135], 11, v[132:133]
	v_lshl_add_u64 v[134:135], s[80:81], 0, v[134:135]
	v_lshl_add_u64 v[134:135], v[134:135], 0, v[130:131]
	v_lshl_add_u64 v[134:135], v[134:135], 0, v[0:1]
	v_lshl_add_u64 v[134:135], v[134:135], 0, v[0:1]
	s_mov_b64 s[2:3], 0x10000
	v_lshl_add_u64 v[136:137], v[134:135], 0, s[2:3]
	v_lshl_add_u64 v[138:139], v[136:137], 0, s[2:3]
	v_lshl_add_u64 v[140:141], v[138:139], 0, s[2:3]
	v_cvt_pk_bf16_f32 v114, v114, v115
	v_cvt_pk_bf16_f32 v115, v116, v117
	v_cvt_pk_bf16_f32 v116, v118, v119
	v_cvt_pk_bf16_f32 v117, v120, v121
	v_cvt_pk_bf16_f32 v118, v122, v123
	v_cvt_pk_bf16_f32 v119, v124, v125
	v_cvt_pk_bf16_f32 v120, v126, v127
	v_cvt_pk_bf16_f32 v121, v128, v129
	v_cvt_pk_bf16_f32 v98, v98, v99
	v_cvt_pk_bf16_f32 v99, v100, v101
	v_cvt_pk_bf16_f32 v100, v102, v103
	v_cvt_pk_bf16_f32 v101, v104, v105
	v_cvt_pk_bf16_f32 v102, v106, v107
	v_cvt_pk_bf16_f32 v103, v108, v109
	v_cvt_pk_bf16_f32 v104, v110, v111
	v_cvt_pk_bf16_f32 v105, v112, v113
	v_permlane32_swap_b32 v114, v116
	v_permlane32_swap_b32 v115, v117
	v_permlane32_swap_b32 v118, v120
	v_permlane32_swap_b32 v119, v121
	global_store_dwordx4 v[134:135], v[114:117], off
	global_store_dwordx4 v[134:135], v[118:121], off offset:32
	v_cvt_pk_bf16_f32 v82, v82, v83
	v_cvt_pk_bf16_f32 v83, v84, v85
	v_cvt_pk_bf16_f32 v84, v86, v87
	v_cvt_pk_bf16_f32 v85, v88, v89
	v_cvt_pk_bf16_f32 v86, v90, v91
	v_cvt_pk_bf16_f32 v87, v92, v93
	v_cvt_pk_bf16_f32 v88, v94, v95
	v_cvt_pk_bf16_f32 v89, v96, v97
	v_permlane32_swap_b32 v98, v100
	v_permlane32_swap_b32 v99, v101
	v_permlane32_swap_b32 v102, v104
	v_permlane32_swap_b32 v103, v105
	global_store_dwordx4 v[134:135], v[98:101], off offset:64
	global_store_dwordx4 v[134:135], v[102:105], off offset:96
	v_cvt_pk_bf16_f32 v66, v66, v67
	v_cvt_pk_bf16_f32 v67, v68, v69
	v_cvt_pk_bf16_f32 v68, v70, v71
	v_cvt_pk_bf16_f32 v69, v72, v73
	v_cvt_pk_bf16_f32 v70, v74, v75
	v_cvt_pk_bf16_f32 v71, v76, v77
	v_cvt_pk_bf16_f32 v72, v78, v79
	v_cvt_pk_bf16_f32 v73, v80, v81
	v_permlane32_swap_b32 v82, v84
	v_permlane32_swap_b32 v83, v85
	v_permlane32_swap_b32 v86, v88
	v_permlane32_swap_b32 v87, v89
	global_store_dwordx4 v[136:137], v[82:85], off
	global_store_dwordx4 v[136:137], v[86:89], off offset:32
	v_cvt_pk_bf16_f32 v50, v50, v51
	v_cvt_pk_bf16_f32 v51, v52, v53
	v_cvt_pk_bf16_f32 v52, v54, v55
	v_cvt_pk_bf16_f32 v53, v56, v57
	v_cvt_pk_bf16_f32 v54, v58, v59
	v_cvt_pk_bf16_f32 v55, v60, v61
	v_cvt_pk_bf16_f32 v56, v62, v63
	v_cvt_pk_bf16_f32 v57, v64, v65
	v_permlane32_swap_b32 v66, v68
	v_permlane32_swap_b32 v67, v69
	v_permlane32_swap_b32 v70, v72
	v_permlane32_swap_b32 v71, v73
	global_store_dwordx4 v[136:137], v[66:69], off offset:64
	global_store_dwordx4 v[136:137], v[70:73], off offset:96
	v_cvt_pk_bf16_f32 v34, v34, v35
	v_cvt_pk_bf16_f32 v35, v36, v37
	v_cvt_pk_bf16_f32 v36, v38, v39
	v_cvt_pk_bf16_f32 v37, v40, v41
	v_cvt_pk_bf16_f32 v38, v42, v43
	v_cvt_pk_bf16_f32 v39, v44, v45
	v_cvt_pk_bf16_f32 v40, v46, v47
	v_cvt_pk_bf16_f32 v41, v48, v49
	v_permlane32_swap_b32 v50, v52
	v_permlane32_swap_b32 v51, v53
	v_permlane32_swap_b32 v54, v56
	v_permlane32_swap_b32 v55, v57
	global_store_dwordx4 v[138:139], v[50:53], off
	global_store_dwordx4 v[138:139], v[54:57], off offset:32
	v_cvt_pk_bf16_f32 v18, v18, v19
	v_cvt_pk_bf16_f32 v19, v20, v21
	v_cvt_pk_bf16_f32 v20, v22, v23
	v_cvt_pk_bf16_f32 v21, v24, v25
	v_cvt_pk_bf16_f32 v22, v26, v27
	v_cvt_pk_bf16_f32 v23, v28, v29
	v_cvt_pk_bf16_f32 v24, v30, v31
	v_cvt_pk_bf16_f32 v25, v32, v33
	v_permlane32_swap_b32 v34, v36
	v_permlane32_swap_b32 v35, v37
	v_permlane32_swap_b32 v38, v40
	v_permlane32_swap_b32 v39, v41
	global_store_dwordx4 v[138:139], v[34:37], off offset:64
	global_store_dwordx4 v[138:139], v[38:41], off offset:96
	v_cvt_pk_bf16_f32 v2, v2, v3
	v_cvt_pk_bf16_f32 v3, v4, v5
	v_cvt_pk_bf16_f32 v4, v6, v7
	v_cvt_pk_bf16_f32 v5, v8, v9
	v_cvt_pk_bf16_f32 v6, v10, v11
	v_cvt_pk_bf16_f32 v7, v12, v13
	v_cvt_pk_bf16_f32 v8, v14, v15
	v_cvt_pk_bf16_f32 v9, v16, v17
	v_permlane32_swap_b32 v18, v20
	v_permlane32_swap_b32 v19, v21
	v_permlane32_swap_b32 v22, v24
	v_permlane32_swap_b32 v23, v25
	global_store_dwordx4 v[140:141], v[18:21], off
	global_store_dwordx4 v[140:141], v[22:25], off offset:32
	s_nop 1
	v_permlane32_swap_b32 v2, v4
	v_permlane32_swap_b32 v3, v5
	v_permlane32_swap_b32 v6, v8
	v_permlane32_swap_b32 v7, v9
	global_store_dwordx4 v[140:141], v[2:5], off offset:64
	global_store_dwordx4 v[140:141], v[6:9], off offset:96
	s_add_i32 s0, s0, s46
	v_readlane_b32 s1, v254, 52
	s_nop 3
	v_add_u32_e32 v191, s1, v191
	s_cmpk_gt_i32 s0, 0xff
	s_cbranch_scc0 .LBB0_72
